# v53: v52 + phase-1 gate bias (loop-invariant) loaded once before the row loops instead of per inner trip
# baseline (speedup 1.0000x reference)
; #define LAS __attribute__((address_space(3)))
; __device__ __forceinline__ int opaque_tid() { int t = (int)threadIdx.x; asm volatile("" : "+v"(t)); return t; }
; __device__ void phase1(const Params& p, LAS unsigned char* lds) {
;     const int tid = opaque_tid(), wid = tid >> 6, lane = tid & 63;
;     LAS float* gs = (LAS float*)lds; LAS float* sh = gs + 1024; LAS float* gsc = sh + 1024; LAS float* shc = gsc + 1024; LAS float* WgT = shc + 1024;
;     const float* modp = (const float*)(p.ws + OFF_MODP);
;     bf16_t* AB = (bf16_t*)(p.ws + OFF_AB);
;     if (tid < 64) {
;         unsigned spins = 0;
;         while ((unsigned)__builtin_amdgcn_readfirstlane(__hip_atomic_load((unsigned*)(p.ws + OFF_ACNT), __ATOMIC_RELAXED, __HIP_MEMORY_SCOPE_AGENT)) < gridDim.x) { __builtin_amdgcn_s_sleep(2); if (++spins > (1u << 22)) break; }
;         __builtin_amdgcn_fence(__ATOMIC_ACQUIRE, "agent"); asm volatile("s_waitcnt vmcnt(0)" ::: "memory"); }
;     __syncthreads();
;     for (int job = blockIdx.x; job < 256; job += gridDim.x) {
;         const int b = job >> 5;
;         for (int i = tid; i < 1024; i += 512) {
;             float s0 = p.ada_b[i], s1 = p.ada_b[1024 + i], s2 = p.ada_b[2048 + i], c0 = s0, c1 = s1;
; #pragma unroll
;             for (int ks = 0; ks < 8; ++ks) { const float* mp = modp + (size_t)(ks * 9 + b) * 3072; s0 += mp[i]; s1 += mp[1024 + i]; s2 += mp[2048 + i];
;                 const float* mc = modp + (size_t)(ks * 9 + 8) * 3072; c0 += mc[i]; c1 += mc[1024 + i]; }
;             const float nw = p.norm_w[i];
;             gs[i] = nw * (1.0f + s1); sh[i] = s0; gsc[i] = nw * (1.0f + c1); shc[i] = c0;
;             if ((job & 31) == 0) ((float*)(p.ws + OFF_GATEV))[b * 1024 + i] = s2;
;         }
;         for (int i = tid; i < 16384; i += 512) { const int j = i & 15, k = i >> 4; WgT[j * 1024 + k] = p.in_w[(size_t)k * 8208 + 5120 + j]; }
;         __syncthreads();
;         const int crow = job * 8 + wid; const int cb = crow >> 8;
;         float* gl = (float*)(p.ws + OFF_GL) + (size_t)b * 16 * 2048 + (size_t)lane * 2048; float* gc = (float*)(p.ws + OFF_GC) + (size_t)cb * 16 * 256 + (size_t)lane * 256 + (crow & 255);
;         const int rbase = job * 64 + wid * 8;
.LBB0_87:
	s_or_b64 exec, exec, s[4:5]
	s_load_dwordx16 s[4:19], s[0:1], 0x40
	s_andn2_b64 vcc, exec, s[24:25]
	v_mbcnt_lo_u32_b32 v158, -1, 0
	s_waitcnt lgkmcnt(0)
	s_barrier
	v_writelane_b32 v254, s4, 6
	s_nop 1
	v_writelane_b32 v254, s5, 7
	v_writelane_b32 v254, s6, 8
	v_writelane_b32 v254, s7, 9
	v_writelane_b32 v254, s8, 10
	v_writelane_b32 v254, s9, 11
	v_writelane_b32 v254, s10, 12
	v_writelane_b32 v254, s11, 13
	v_writelane_b32 v254, s12, 14
	v_writelane_b32 v254, s13, 15
	v_writelane_b32 v254, s14, 16
	v_writelane_b32 v254, s15, 17
	v_writelane_b32 v254, s16, 18
	v_writelane_b32 v254, s17, 19
	v_writelane_b32 v254, s18, 20
	v_writelane_b32 v254, s19, 21
	v_writelane_b32 v254, s20, 22
	s_nop 1
	v_writelane_b32 v254, s21, 23
	s_cbranch_vccnz .LBB0_113
	s_waitcnt vmcnt(1)
	v_mbcnt_hi_u32_b32 v4, -1, v158
	v_and_b32_e32 v7, 64, v4
	v_xor_b32_e32 v5, 32, v4
	v_add_u32_e32 v7, 64, v7
	v_cmp_lt_i32_e32 vcc, v5, v7
	v_and_b32_e32 v6, 63, v32
	v_mov_b32_e32 v35, 0
	v_cndmask_b32_e32 v5, v4, v5, vcc
	v_lshlrev_b32_e32 v53, 2, v5
	v_xor_b32_e32 v5, 16, v4
	v_cmp_lt_i32_e32 vcc, v5, v7
	v_lshlrev_b32_e32 v34, 13, v6
	v_lshlrev_b32_e32 v0, 10, v6
	v_cndmask_b32_e32 v5, v4, v5, vcc
	v_lshlrev_b32_e32 v94, 2, v5
	v_xor_b32_e32 v5, 8, v4
	v_cmp_lt_i32_e32 vcc, v5, v7
	v_mov_b32_e32 v1, v35
	s_mov_b64 s[18:19], 0xfc00000
	v_cndmask_b32_e32 v5, v4, v5, vcc
	v_lshlrev_b32_e32 v95, 2, v5
	v_xor_b32_e32 v5, 4, v4
	v_cmp_lt_i32_e32 vcc, v5, v7
	v_lshl_add_u64 v[0:1], s[70:71], 0, v[0:1]
	v_readlane_b32 s52, v254, 6
	v_cndmask_b32_e32 v5, v4, v5, vcc
	v_lshlrev_b32_e32 v96, 2, v5
	v_xor_b32_e32 v5, 2, v4
	v_cmp_lt_i32_e32 vcc, v5, v7
	s_movk_i32 s3, 0x4000
	v_lshlrev_b32_e32 v2, 2, v6
	v_cndmask_b32_e32 v5, v4, v5, vcc
	v_lshlrev_b32_e32 v97, 2, v5
	v_xor_b32_e32 v5, 1, v4
	v_cmp_lt_i32_e32 vcc, v5, v7
	v_mov_b32_e32 v3, v35
	v_readlane_b32 s53, v254, 7
	v_cndmask_b32_e32 v4, v4, v5, vcc
	v_lshlrev_b32_e32 v98, 2, v4
	v_lshlrev_b32_e32 v4, 3, v6
	v_mov_b32_e32 v5, v35
	v_lshl_add_u64 v[36:37], s[70:71], 0, v[4:5]
	v_and_b32_e32 v4, 8, v32
	v_cmp_eq_u32_e64 s[6:7], 0, v4
	v_and_b32_e32 v4, 4, v32
	v_cmp_eq_u32_e64 s[8:9], 0, v4
	v_cmp_ne_u32_e64 s[10:11], 0, v4
	v_and_b32_e32 v4, 2, v32
	v_cmp_eq_u32_e64 s[12:13], 0, v4
	v_and_b32_e32 v4, 1, v32
	v_cmp_eq_u32_e64 s[14:15], 0, v4
	v_lshl_add_u64 v[4:5], s[70:71], 0, v[34:35]
	v_lshl_add_u64 v[40:41], v[4:5], 0, s[18:19]
	s_mov_b64 s[18:19], 0xfd00000
	v_lshl_add_u64 v[42:43], v[0:1], 0, s[18:19]
	v_max_i32_e32 v0, 0x3e00, v32
	v_sub_u32_e32 v0, v0, v32
	v_add_u32_e32 v0, 0x1ff, v0
	v_lshrrev_b32_e32 v1, 9, v0
	v_cmp_gt_i32_e64 s[4:5], s3, v32
	v_lshl_add_u64 v[44:45], s[52:53], 0, v[2:3]
	s_movk_i32 s3, 0x1ff
	v_add_u32_e32 v3, 1, v1
	v_add_u32_e32 v1, -1, v1
	v_ashrrev_i32_e32 v39, 6, v32
	v_lshrrev_b32_e32 v4, 1, v1
	v_cmp_lt_u32_e64 s[18:19], s3, v0
	v_and_b32_e32 v0, 0xfffffe, v3
	v_cmp_lt_u32_e64 s[20:21], 1, v1
	v_and_b32_e32 v1, 2, v1
	s_movk_i32 s0, 0x400
	v_lshlrev_b32_e32 v51, 3, v39
	v_lshl_add_u32 v99, v6, 4, 0
	v_and_b32_e32 v38, 15, v32
	s_add_u32 s42, s70, 0xfef9000
	v_add_u32_e32 v4, 1, v4
	v_lshl_add_u32 v102, v0, 9, v32
	v_cmp_eq_u32_e64 s[22:23], 0, v1
	v_cmp_ne_u32_e64 s[24:25], v3, v0
	v_ashrrev_i32_e32 v1, 31, v32
	v_mov_b32_e32 v0, v32
	v_cmp_gt_i32_e64 s[0:1], s0, v32
	v_add_u32_e32 v100, 0x4000, v99
	v_cmp_gt_u32_e64 s[16:17], 16, v6
	v_lshl_add_u32 v101, v38, 12, 0
	s_addc_u32 s43, s71, 0
	v_add_u32_e32 v33, 0x200, v32
	v_and_b32_e32 v103, -2, v4
	v_lshl_add_u32 v104, v32, 2, 0
	v_lshlrev_b64 v[46:47], 2, v[0:1]
	s_and_b32 s93, s2, 7
	s_lshl_b32 s93, s93, 5
	s_lshr_b32 s94, s2, 3
	s_add_u32 s93, s93, s94
	v_lshl_add_u32 v105, s93, 6, v51
	s_lshl_b32 s26, s72, 6
	s_mov_b32 s27, 0x8040
	s_movk_i32 s33, 0x5000
	v_lshlrev_b32_e32 v48, 2, v2
	s_mov_b32 s46, 0x3a800000
	s_mov_b32 s34, 0x800000
	s_mov_b32 s35, 0xbfb8aa3b
	s_mov_b32 s47, 0xb2a5705f
	s_mov_b32 s53, 0x42ce8ed0
	s_mov_b32 s75, 0xc2b17218
	s_mov_b32 s77, 0x7f800000
	s_mov_b32 s79, 0x3f2aaaab
; __device__ __forceinline__ void norm_rows2(const f32x4 (&xa)[4], const f32x4 (&xb)[4], const LAS float* gsa, const LAS float* sha, const LAS float* gsb, const LAS float* shb, const LAS float* WgT, ...
;     ...
;     if (lane < 16) { const float gbv = gate_b[lane]; const bool ls = (lane >> 2) & 1;
; __device__ void phase1(const Params& p, LAS unsigned char* lds) {
;     ...
;         for (int i = tid; i < 16384; i += 512) { const int j = i & 15, k = i >> 4; WgT[j * 1024 + k] = p.in_w[(size_t)k * 8208 + 5120 + j]; }
	s_mov_b32 s52, 0x3e9b6dac
	s_mov_b32 s74, 0x3f2aaada
	s_mov_b32 s76, 0x3f317218
	s_mov_b32 s78, 0xb102e308
	s_mov_b32 s92, 0x33800000
	v_mov_b32_e32 v106, 2
	v_mov_b32_e32 v50, 0x358637bd
	v_mov_b32_e32 v107, 0x7f800000
	v_mov_b32_e32 v52, 0x3ecc95a3
	v_readlane_b32 s54, v254, 8
	v_readlane_b32 s55, v254, 9
	v_readlane_b32 s56, v254, 10
	v_readlane_b32 s57, v254, 11
	v_readlane_b32 s58, v254, 12
	v_readlane_b32 s59, v254, 13
	v_readlane_b32 s60, v254, 14
	v_readlane_b32 s61, v254, 15
	v_readlane_b32 s62, v254, 16
	v_readlane_b32 s63, v254, 17
	v_readlane_b32 s64, v254, 18
	v_readlane_b32 s65, v254, 19
	v_readlane_b32 s66, v254, 20
	v_readlane_b32 s67, v254, 21
	s_and_saveexec_b64 s[28:29], s[16:17]
	global_load_dword v244, v[44:45], off
	s_or_b64 exec, exec, s[28:29]
	v_lshrrev_b32_e32 v110, 4, v32
	v_mul_u32_u24_e32 v111, 0x8040, v110
	v_lshl_add_u32 v111, v38, 2, v111
	v_add_u32_e32 v111, 0x5000, v111
	v_lshl_add_u32 v110, v110, 2, v101
	s_mov_b64 s[38:39], s[50:51]
	global_load_dword v112, v111, s[38:39]
	s_add_u32 s38, s38, 0x100800
	s_addc_u32 s39, s39, 0
	global_load_dword v113, v111, s[38:39]
	s_add_u32 s38, s38, 0x100800
	s_addc_u32 s39, s39, 0
	global_load_dword v114, v111, s[38:39]
	s_add_u32 s38, s38, 0x100800
	s_addc_u32 s39, s39, 0
	global_load_dword v115, v111, s[38:39]
	s_add_u32 s38, s38, 0x100800
	s_addc_u32 s39, s39, 0
	global_load_dword v116, v111, s[38:39]
	s_add_u32 s38, s38, 0x100800
	s_addc_u32 s39, s39, 0
	global_load_dword v117, v111, s[38:39]
	s_add_u32 s38, s38, 0x100800
	s_addc_u32 s39, s39, 0
	global_load_dword v118, v111, s[38:39]
	s_add_u32 s38, s38, 0x100800
	s_addc_u32 s39, s39, 0
	global_load_dword v119, v111, s[38:39]
	s_add_u32 s38, s38, 0x100800
	s_addc_u32 s39, s39, 0
	global_load_dword v120, v111, s[38:39]
	s_add_u32 s38, s38, 0x100800
	s_addc_u32 s39, s39, 0
	global_load_dword v121, v111, s[38:39]
	s_add_u32 s38, s38, 0x100800
	s_addc_u32 s39, s39, 0
	global_load_dword v122, v111, s[38:39]
	s_add_u32 s38, s38, 0x100800
	s_addc_u32 s39, s39, 0
	global_load_dword v123, v111, s[38:39]
	s_add_u32 s38, s38, 0x100800
	s_addc_u32 s39, s39, 0
	global_load_dword v124, v111, s[38:39]
	s_add_u32 s38, s38, 0x100800
	s_addc_u32 s39, s39, 0
	global_load_dword v125, v111, s[38:39]
	s_add_u32 s38, s38, 0x100800
	s_addc_u32 s39, s39, 0
	global_load_dword v126, v111, s[38:39]
	s_add_u32 s38, s38, 0x100800
	s_addc_u32 s39, s39, 0
	global_load_dword v127, v111, s[38:39]
	s_add_u32 s38, s38, 0x100800
	s_addc_u32 s39, s39, 0
	global_load_dword v128, v111, s[38:39]
	s_add_u32 s38, s38, 0x100800
	s_addc_u32 s39, s39, 0
	global_load_dword v129, v111, s[38:39]
	s_add_u32 s38, s38, 0x100800
	s_addc_u32 s39, s39, 0
	global_load_dword v130, v111, s[38:39]
	s_add_u32 s38, s38, 0x100800
	s_addc_u32 s39, s39, 0
	global_load_dword v131, v111, s[38:39]
	s_add_u32 s38, s38, 0x100800
	s_addc_u32 s39, s39, 0
	global_load_dword v132, v111, s[38:39]
	s_add_u32 s38, s38, 0x100800
	s_addc_u32 s39, s39, 0
	global_load_dword v133, v111, s[38:39]
	s_add_u32 s38, s38, 0x100800
	s_addc_u32 s39, s39, 0
	global_load_dword v134, v111, s[38:39]
	s_add_u32 s38, s38, 0x100800
	s_addc_u32 s39, s39, 0
	global_load_dword v135, v111, s[38:39]
	s_add_u32 s38, s38, 0x100800
	s_addc_u32 s39, s39, 0
	global_load_dword v136, v111, s[38:39]
	s_add_u32 s38, s38, 0x100800
	s_addc_u32 s39, s39, 0
	global_load_dword v137, v111, s[38:39]
	s_add_u32 s38, s38, 0x100800
	s_addc_u32 s39, s39, 0
	global_load_dword v138, v111, s[38:39]
	s_add_u32 s38, s38, 0x100800
	s_addc_u32 s39, s39, 0
	global_load_dword v139, v111, s[38:39]
	s_add_u32 s38, s38, 0x100800
	s_addc_u32 s39, s39, 0
	global_load_dword v140, v111, s[38:39]
	s_add_u32 s38, s38, 0x100800
	s_addc_u32 s39, s39, 0
	global_load_dword v141, v111, s[38:39]
	s_add_u32 s38, s38, 0x100800
	s_addc_u32 s39, s39, 0
	global_load_dword v142, v111, s[38:39]
	s_add_u32 s38, s38, 0x100800
	s_addc_u32 s39, s39, 0
	global_load_dword v143, v111, s[38:39]
	s_branch .LBB0_90

; __device__ __forceinline__ float dot4(const f32x4 a, const f32x4 b) { return (a[0] * b[0] + a[1] * b[1]) + (a[2] * b[2] + a[3] * b[3]); }
; __device__ __forceinline__ void norm_rows2(const f32x4 (&xa)[4], const f32x4 (&xb)[4], const LAS float* gsa, const LAS float* sha, const LAS float* gsb, const LAS float* shb, const LAS float* WgT, ...
;     float ssa = 0.f, ssb = 0.f;
; #pragma unroll
;     for (int i = 0; i < 4; ++i) { ssa += dot4(xa[i], xa[i]); ssb += dot4(xb[i], xb[i]); }
;     ssa = wave_sum(ssa); ssb = wave_sum(ssb);
;     const float ra = rsqrtf(ssa * (1.0f / 1024.0f) + 1e-6f), rb = rsqrtf(ssb * (1.0f / 1024.0f) + 1e-6f);
; __device__ void phase1(const Params& p, LAS unsigned char* lds) {
;     ...
;             const int ra_ = pr < 4 ? rbase + 2 * pr : rbase + 7;
;             const float* xa_ = p.x + (size_t)ra_ * 1024; const float* xb_ = pr < 4 ? xa_ + 1024 : p.ctx + (size_t)crow * 1024;
;             f32x4 xa[4], xb[4];
; #pragma unroll
;             for (int i = 0; i < 4; ++i) { xa[i] = __builtin_nontemporal_load((const f32x4*)(xa_ + i * 256 + lane * 4)); xb[i] = __builtin_nontemporal_load((const f32x4*)(xb_ + i * 256 + lane * 4)); }
.LBB0_110:
	s_add_i32 s28, 0, 0x2000
	s_add_i32 s29, 0, 0x3000
	s_add_i32 s30, 0, 0x1000
	s_cmp_eq_u32 s82, 8
	v_add_u32_e32 v0, s82, v105
	s_cselect_b64 vcc, -1, 0
	v_cndmask_b32_e32 v60, v0, v108, vcc
	v_ashrrev_i32_e32 v61, 31, v60
	v_lshlrev_b64 v[0:1], 12, v[60:61]
	v_lshl_add_u64 v[0:1], s[36:37], 0, v[0:1]
	v_mov_b32_e32 v49, v35
	s_waitcnt lgkmcnt(0)
	v_lshl_add_u64 v[2:3], v[0:1], 0, v[48:49]
	s_mov_b64 s[38:39], 0x1000
	global_load_dwordx4 v[24:27], v[2:3], off nt
	global_load_dwordx4 v[20:23], v[2:3], off offset:1024 nt
	global_load_dwordx4 v[4:7], v[2:3], off offset:3072 nt
	global_load_dwordx4 v[12:15], v[2:3], off offset:2048 nt
	v_lshl_add_u64 v[0:1], v[0:1], 0, s[38:39]
	v_cndmask_b32_e32 v1, v1, v59, vcc
	v_cndmask_b32_e32 v0, v0, v58, vcc
	v_lshl_add_u64 v[8:9], v[0:1], 0, v[48:49]
	global_load_dwordx4 v[28:31], v[8:9], off nt
	global_load_dwordx4 v[16:19], v[8:9], off offset:1024 nt
	global_load_dwordx4 v[0:3], v[8:9], off offset:3072 nt
	s_nop 0
	global_load_dwordx4 v[8:11], v[8:9], off offset:2048 nt
	s_and_b64 s[38:39], vcc, exec
	s_cselect_b32 s28, s28, 0
	s_cselect_b32 s29, s29, s30
	s_waitcnt vmcnt(7)
	v_pk_mul_f32 v[62:63], v[26:27], v[26:27]
	v_pk_mul_f32 v[64:65], v[24:25], v[24:25]
	s_waitcnt vmcnt(6)
	v_pk_mul_f32 v[66:67], v[22:23], v[22:23]
	v_pk_mul_f32 v[68:69], v[20:21], v[20:21]
	s_waitcnt vmcnt(4)
	v_mul_f32_e32 v70, v15, v15
	v_pk_mov_b32 v[72:73], v[64:65], v[62:63] op_sel:[1,0]
	v_mov_b32_e32 v65, v63
	v_pk_mov_b32 v[62:63], v[68:69], v[66:67] op_sel:[1,0]
	v_mov_b32_e32 v69, v67
	v_mul_f32_e32 v80, v7, v7
	v_mul_f32_e32 v34, v13, v13
	v_pk_fma_f32 v[70:71], v[14:15], v[14:15], v[70:71] op_sel_hi:[1,1,0]
	v_pk_add_f32 v[64:65], v[72:73], v[64:65]
	s_waitcnt vmcnt(3)
	v_pk_mul_f32 v[72:73], v[30:31], v[30:31]
	v_pk_mul_f32 v[74:75], v[28:29], v[28:29]
	v_pk_add_f32 v[62:63], v[62:63], v[68:69]
	s_waitcnt vmcnt(2)
	v_pk_mul_f32 v[68:69], v[18:19], v[18:19]
	v_pk_mul_f32 v[76:77], v[16:17], v[16:17]
	v_mul_f32_e32 v49, v4, v4
	v_mul_f32_e32 v79, v5, v5
	v_mul_f32_e32 v78, v6, v6
	v_pk_fma_f32 v[66:67], v[12:13], v[12:13], v[34:35] op_sel_hi:[1,1,0]
	v_mov_b32_e32 v71, v80
	v_pk_mov_b32 v[80:81], v[74:75], v[72:73] op_sel:[1,0]
	v_mov_b32_e32 v75, v73
	v_pk_mov_b32 v[72:73], v[76:77], v[68:69] op_sel:[1,0]
	v_mov_b32_e32 v77, v69
	v_pk_add_f32 v[64:65], v[64:65], v[64:65] op_sel:[0,1] op_sel_hi:[1,0]
	v_pk_add_f32 v[62:63], v[62:63], v[62:63] op_sel:[0,1] op_sel_hi:[1,0]
	v_mov_b32_e32 v67, v78
	s_waitcnt vmcnt(0)
	v_mul_f32_e32 v34, v9, v9
	v_mul_f32_e32 v78, v11, v11
	v_pk_add_f32 v[74:75], v[80:81], v[74:75]
	v_pk_add_f32 v[72:73], v[72:73], v[76:77]
	v_mov_b32_e32 v65, v49
	v_mov_b32_e32 v63, v79
	v_mul_f32_e32 v82, v0, v0
	v_mul_f32_e32 v83, v1, v1
	v_mul_f32_e32 v84, v2, v2
	v_mul_f32_e32 v85, v3, v3
	v_pk_add_f32 v[66:67], v[66:67], v[70:71]
	v_pk_fma_f32 v[68:69], v[8:9], v[8:9], v[34:35] op_sel_hi:[1,1,0]
	v_pk_fma_f32 v[70:71], v[10:11], v[10:11], v[78:79] op_sel_hi:[1,1,0]
	v_pk_add_f32 v[62:63], v[64:65], v[62:63]
	v_pk_add_f32 v[64:65], v[74:75], v[74:75] op_sel:[0,1] op_sel_hi:[1,0]
	v_pk_add_f32 v[72:73], v[72:73], v[72:73] op_sel:[0,1] op_sel_hi:[1,0]
	v_mov_b32_e32 v69, v84
	v_mov_b32_e32 v71, v85
	v_mov_b32_e32 v65, v82
	v_mov_b32_e32 v73, v83
	v_pk_add_f32 v[68:69], v[68:69], v[70:71]
	v_pk_add_f32 v[64:65], v[64:65], v[72:73]
	v_pk_add_f32 v[62:63], v[62:63], v[66:67]
	v_pk_add_f32 v[64:65], v[64:65], v[68:69]
	v_mov_b32_e32 v67, v62
	v_mov_b32_e32 v66, v64
	v_mov_b32_e32 v62, v65
	v_pk_add_f32 v[62:63], v[66:67], v[62:63]
	v_lshlrev_b64 v[76:77], 11, v[60:61]
	v_add_u32_e32 v49, s28, v48
	v_add_u32_e32 v61, s29, v48
	v_add_u32_e32 v34, 1, v60
	ds_read_b128 v[64:67], v99
	ds_read_b128 v[68:71], v99 offset:4096
	ds_read_b128 v[80:83], v49
	ds_read_b128 v[84:87], v61
	v_add_f32_dpp v62, v62, v62 row_mirror row_mask:0xf bank_mask:0xf
	v_add_f32_dpp v63, v63, v63 row_mirror row_mask:0xf bank_mask:0xf
	v_cndmask_b32_e32 v74, v34, v109, vcc
	v_add_f32_dpp v62, v62, v62 row_half_mirror row_mask:0xf bank_mask:0xf
	v_add_f32_dpp v63, v63, v63 row_half_mirror row_mask:0xf bank_mask:0xf
	v_ashrrev_i32_e32 v75, 31, v74
	v_add_f32_dpp v62, v62, v62 quad_perm:[1,0,3,2] row_mask:0xf bank_mask:0xf
	v_add_f32_dpp v63, v63, v63 quad_perm:[1,0,3,2] row_mask:0xf bank_mask:0xf
	v_lshlrev_b64 v[74:75], 11, v[74:75]
	v_add_f32_dpp v62, v62, v62 quad_perm:[2,3,0,1] row_mask:0xf bank_mask:0xf
	v_add_f32_dpp v63, v63, v63 quad_perm:[2,3,0,1] row_mask:0xf bank_mask:0xf
	v_lshl_add_u64 v[78:79], v[36:37], 0, v[76:77]
	s_nop 0
	v_readlane_b32 s54, v62, 0
	v_readlane_b32 s55, v62, 16
	v_readlane_b32 s56, v62, 32
	v_readlane_b32 s57, v62, 48
	v_readlane_b32 s58, v63, 0
	v_readlane_b32 s59, v63, 16
	v_readlane_b32 s60, v63, 32
	v_readlane_b32 s61, v63, 48
	v_mov_b32_e32 v62, s54
	v_mov_b32_e32 v63, s58
	v_add_f32_e32 v62, s55, v62
	v_add_f32_e32 v63, s59, v63
	v_add_f32_e32 v62, s56, v62
	v_add_f32_e32 v63, s60, v63
	v_add_f32_e32 v62, s57, v62
	v_add_f32_e32 v63, s61, v63
	s_waitcnt lgkmcnt(0)
; #define LAS __attribute__((address_space(3)))
; __device__ __forceinline__ unsigned cvt_pk_bf16(float lo, float hi) { unsigned r; asm volatile("v_cvt_pk_bf16_f32 %0, %1, %2" : "=v"(r) : "v"(lo), "v"(hi)); return r; }
; __device__ __forceinline__ float dot4(const f32x4 a, const f32x4 b) { return (a[0] * b[0] + a[1] * b[1]) + (a[2] * b[2] + a[3] * b[3]); }
; __device__ __forceinline__ void norm_rows2(const f32x4 (&xa)[4], const f32x4 (&xb)[4], const LAS float* gsa, const LAS float* sha, const LAS float* gsb, const LAS float* shb, const LAS float* WgT, ...
;     ...
;     const float ra = rsqrtf(ssa * (1.0f / 1024.0f) + 1e-6f), rb = rsqrtf(ssb * (1.0f / 1024.0f) + 1e-6f);
;     f32x4 ya[4], yb[4];
; #pragma unroll
;     for (int i = 0; i < 4; ++i) {
;         ya[i] = xa[i] * ra * *(const LAS f32x4*)(gsa + i * 256 + lane * 4) + *(const LAS f32x4*)(sha + i * 256 + lane * 4);
;         yb[i] = xb[i] * rb * *(const LAS f32x4*)(gsb + i * 256 + lane * 4) + *(const LAS f32x4*)(shb + i * 256 + lane * 4);
;         u32x2 w; w.x = cvt_pk_bf16(ya[i][0], ya[i][1]); w.y = cvt_pk_bf16(ya[i][2], ya[i][3]); *(u32x2*)(oa + i * 256 + lane * 4) = w;
;         u32x2 v; v.x = cvt_pk_bf16(yb[i][0], yb[i][1]); v.y = cvt_pk_bf16(yb[i][2], yb[i][3]); *(u32x2*)(ob + i * 256 + lane * 4) = v; }
;     f32x4 pa[4], pb[4];
; #pragma unroll
;     for (int jq = 0; jq < 4; ++jq) { f32x4 sa = (f32x4){0.f, 0.f, 0.f, 0.f}, sb = sa;
; #pragma unroll
;         for (int i = 0; i < 4; ++i) { const LAS float* wp = WgT + (jq * 4) * 1024 + i * 256 + lane * 4;
;             const f32x4 w0 = *(const LAS f32x4*)wp, w1 = *(const LAS f32x4*)(wp + 1024), w2 = *(const LAS f32x4*)(wp + 2048), w3 = *(const LAS f32x4*)(wp + 3072);
;             sa += (f32x4){dot4(ya[i], w0), dot4(ya[i], w1), dot4(ya[i], w2), dot4(ya[i], w3)};
;             sb += (f32x4){dot4(yb[i], w0), dot4(yb[i], w1), dot4(yb[i], w2), dot4(yb[i], w3)}; }
	s_nop 0
	v_pk_fma_f32 v[62:63], v[62:63], s[46:47], v[50:51] op_sel_hi:[1,0,0]
	s_nop 0
	v_mul_f32_e32 v72, 0x4b800000, v63
	v_cmp_gt_f32_e64 s[28:29], s34, v63
	v_mul_f32_e32 v73, 0x4b800000, v62
	v_cmp_gt_f32_e64 s[30:31], s34, v62
	v_cndmask_b32_e64 v63, v63, v72, s[28:29]
	v_rsq_f32_e32 v72, v63
	v_cndmask_b32_e64 v62, v62, v73, s[30:31]
	v_rsq_f32_e32 v73, v62
	v_lshl_add_u64 v[62:63], v[36:37], 0, v[74:75]
	v_mul_f32_e32 v74, 0x45800000, v72
	v_cndmask_b32_e64 v88, v72, v74, s[28:29]
	v_mul_f32_e32 v75, 0x45800000, v73
	v_cndmask_b32_e64 v90, v73, v75, s[30:31]
	v_pk_mul_f32 v[24:25], v[24:25], v[88:89] op_sel_hi:[1,0]
	v_pk_mul_f32 v[26:27], v[26:27], v[88:89] op_sel_hi:[1,0]
	v_pk_mul_f32 v[28:29], v[28:29], v[90:91] op_sel_hi:[1,0]
	v_pk_mul_f32 v[30:31], v[30:31], v[90:91] op_sel_hi:[1,0]
	v_pk_mul_f32 v[92:93], v[20:21], v[88:89] op_sel_hi:[1,0]
	v_pk_fma_f32 v[74:75], v[66:67], v[26:27], v[70:71]
	v_pk_fma_f32 v[76:77], v[64:65], v[24:25], v[68:69]
	v_pk_mul_f32 v[110:111], v[22:23], v[88:89] op_sel_hi:[1,0]
	v_cvt_pk_bf16_f32 v20, v76, v77
	v_cvt_pk_bf16_f32 v21, v74, v75
	v_pk_fma_f32 v[70:71], v[82:83], v[30:31], v[86:87]
	v_pk_fma_f32 v[72:73], v[80:81], v[28:29], v[84:85]
	global_store_dwordx2 v[78:79], v[20:21], off
	v_cvt_pk_bf16_f32 v64, v72, v73
	v_cvt_pk_bf16_f32 v65, v70, v71
	ds_read_b128 v[20:23], v99 offset:1024
	ds_read_b128 v[24:27], v99 offset:5120
	ds_read_b128 v[28:31], v49 offset:1024
	ds_read_b128 v[80:83], v61 offset:1024
	v_pk_mul_f32 v[16:17], v[16:17], v[90:91] op_sel_hi:[1,0]
	global_store_dwordx2 v[62:63], v[64:65], off
	v_pk_mul_f32 v[18:19], v[18:19], v[90:91] op_sel_hi:[1,0]
	s_waitcnt lgkmcnt(2)
	v_pk_fma_f32 v[66:67], v[110:111], v[22:23], v[26:27]
	v_pk_fma_f32 v[68:69], v[92:93], v[20:21], v[24:25]
	s_waitcnt lgkmcnt(0)
	v_pk_fma_f32 v[64:65], v[16:17], v[28:29], v[80:81]
	v_cvt_pk_bf16_f32 v16, v68, v69
	v_cvt_pk_bf16_f32 v17, v66, v67
	v_pk_fma_f32 v[30:31], v[18:19], v[30:31], v[82:83]
	global_store_dwordx2 v[78:79], v[16:17], off offset:512
	v_cvt_pk_bf16_f32 v16, v64, v65
	v_cvt_pk_bf16_f32 v17, v30, v31
	global_store_dwordx2 v[62:63], v[16:17], off offset:512
	ds_read_b128 v[16:19], v99 offset:2048
	ds_read_b128 v[20:23], v99 offset:6144
	ds_read_b128 v[24:27], v49 offset:2048
	ds_read_b128 v[80:83], v61 offset:2048
	v_pk_mul_f32 v[12:13], v[12:13], v[88:89] op_sel_hi:[1,0]
	v_pk_mul_f32 v[14:15], v[14:15], v[88:89] op_sel_hi:[1,0]
	v_pk_mul_f32 v[8:9], v[8:9], v[90:91] op_sel_hi:[1,0]
	s_waitcnt lgkmcnt(2)
	v_pk_fma_f32 v[14:15], v[14:15], v[18:19], v[22:23]
	v_pk_fma_f32 v[18:19], v[12:13], v[16:17], v[20:21]
	v_pk_mul_f32 v[10:11], v[10:11], v[90:91] op_sel_hi:[1,0]
	s_waitcnt lgkmcnt(0)
	v_pk_fma_f32 v[20:21], v[8:9], v[24:25], v[80:81]
	v_cvt_pk_bf16_f32 v8, v18, v19
	v_cvt_pk_bf16_f32 v9, v14, v15
	v_pk_fma_f32 v[16:17], v[10:11], v[26:27], v[82:83]
	global_store_dwordx2 v[78:79], v[8:9], off offset:1024
	v_cvt_pk_bf16_f32 v8, v20, v21
	v_cvt_pk_bf16_f32 v9, v16, v17
	global_store_dwordx2 v[62:63], v[8:9], off offset:1024
	ds_read_b128 v[8:11], v99 offset:3072
	ds_read_b128 v[22:25], v99 offset:7168
	v_pk_mul_f32 v[12:13], v[4:5], v[88:89] op_sel_hi:[1,0]
	v_pk_mul_f32 v[80:81], v[6:7], v[88:89] op_sel_hi:[1,0]
	ds_read_b128 v[4:7], v49 offset:3072
	ds_read_b128 v[26:29], v61 offset:3072
	v_pk_mul_f32 v[0:1], v[0:1], v[90:91] op_sel_hi:[1,0]
	s_waitcnt lgkmcnt(2)
	v_pk_fma_f32 v[10:11], v[80:81], v[10:11], v[24:25]
	v_pk_fma_f32 v[12:13], v[12:13], v[8:9], v[22:23]
	v_pk_mul_f32 v[2:3], v[2:3], v[90:91] op_sel_hi:[1,0]
	s_waitcnt lgkmcnt(0)
	v_pk_fma_f32 v[8:9], v[0:1], v[4:5], v[26:27]
	v_cvt_pk_bf16_f32 v0, v12, v13
	v_cvt_pk_bf16_f32 v1, v10, v11
	v_pk_fma_f32 v[6:7], v[2:3], v[6:7], v[28:29]
	global_store_dwordx2 v[78:79], v[0:1], off offset:1536
	v_cvt_pk_bf16_f32 v4, v8, v9
	v_cvt_pk_bf16_f32 v5, v6, v7
	global_store_dwordx2 v[62:63], v[4:5], off offset:1536
	ds_read_b128 v[110:113], v99 offset:16384
	ds_read_b128 v[114:117], v99 offset:20480
	ds_read_b128 v[118:121], v99 offset:24576
	ds_read_b128 v[122:125], v99 offset:28672
	ds_read_b128 v[126:129], v99 offset:32768
	ds_read_b128 v[130:133], v99 offset:36864
	ds_read_b128 v[134:137], v99 offset:40960
	ds_read_b128 v[138:141], v99 offset:45056
	ds_read_b128 v[142:145], v99 offset:49152
	ds_read_b128 v[146:149], v99 offset:53248
	ds_read_b128 v[150:153], v99 offset:57344
	ds_read_b128 v[154:157], v99 offset:61440
	s_waitcnt lgkmcnt(8)
	v_pk_mul_f32 v[160:161], v[72:73], v[110:111]
	v_pk_mul_f32 v[192:193], v[76:77], v[110:111]
	v_pk_mul_f32 v[162:163], v[72:73], v[114:115]
	v_pk_mul_f32 v[194:195], v[76:77], v[114:115]
	v_pk_mul_f32 v[164:165], v[72:73], v[118:119]
	v_pk_mul_f32 v[196:197], v[76:77], v[118:119]
	v_pk_mul_f32 v[166:167], v[72:73], v[122:123]
	v_pk_mul_f32 v[198:199], v[76:77], v[122:123]
	v_pk_fma_f32 v[160:161], v[70:71], v[112:113], v[160:161]
	v_pk_fma_f32 v[192:193], v[74:75], v[112:113], v[192:193]
	v_pk_fma_f32 v[162:163], v[70:71], v[116:117], v[162:163]
	v_pk_fma_f32 v[194:195], v[74:75], v[116:117], v[194:195]
	v_pk_fma_f32 v[164:165], v[70:71], v[120:121], v[164:165]
	v_pk_fma_f32 v[196:197], v[74:75], v[120:121], v[196:197]
	v_pk_fma_f32 v[166:167], v[70:71], v[124:125], v[166:167]
	v_pk_fma_f32 v[198:199], v[74:75], v[124:125], v[198:199]
	ds_read_b128 v[228:231], v100 offset:49152
	ds_read_b128 v[232:235], v100 offset:53248
	ds_read_b128 v[236:239], v100 offset:57344
	ds_read_b128 v[240:243], v100 offset:61440
	s_waitcnt lgkmcnt(8)
; #define LAS __attribute__((address_space(3)))
; __device__ __forceinline__ float dot4(const f32x4 a, const f32x4 b) { return (a[0] * b[0] + a[1] * b[1]) + (a[2] * b[2] + a[3] * b[3]); }
; __device__ __forceinline__ void norm_rows2(const f32x4 (&xa)[4], const f32x4 (&xb)[4], const LAS float* gsa, const LAS float* sha, const LAS float* gsb, const LAS float* shb, const LAS float* WgT, ...
;     ...
;     for (int jq = 0; jq < 4; ++jq) { f32x4 sa = (f32x4){0.f, 0.f, 0.f, 0.f}, sb = sa;
; #pragma unroll
;         for (int i = 0; i < 4; ++i) { const LAS float* wp = WgT + (jq * 4) * 1024 + i * 256 + lane * 4;
;             const f32x4 w0 = *(const LAS f32x4*)wp, w1 = *(const LAS f32x4*)(wp + 1024), w2 = *(const LAS f32x4*)(wp + 2048), w3 = *(const LAS f32x4*)(wp + 3072);
;             sa += (f32x4){dot4(ya[i], w0), dot4(ya[i], w1), dot4(ya[i], w2), dot4(ya[i], w3)};
;             sb += (f32x4){dot4(yb[i], w0), dot4(yb[i], w1), dot4(yb[i], w2), dot4(yb[i], w3)}; }
;         pa[jq] = sa; pb[jq] = sb; }
	v_pk_mul_f32 v[168:169], v[72:73], v[126:127]
	v_pk_mul_f32 v[200:201], v[76:77], v[126:127]
	v_pk_mul_f32 v[170:171], v[72:73], v[130:131]
	v_pk_mul_f32 v[202:203], v[76:77], v[130:131]
	v_pk_mul_f32 v[172:173], v[72:73], v[134:135]
	v_pk_mul_f32 v[204:205], v[76:77], v[134:135]
	v_pk_mul_f32 v[174:175], v[72:73], v[138:139]
	v_pk_mul_f32 v[206:207], v[76:77], v[138:139]
	v_pk_fma_f32 v[168:169], v[70:71], v[128:129], v[168:169]
	v_pk_fma_f32 v[200:201], v[74:75], v[128:129], v[200:201]
	v_pk_fma_f32 v[170:171], v[70:71], v[132:133], v[170:171]
	v_pk_fma_f32 v[202:203], v[74:75], v[132:133], v[202:203]
	v_pk_fma_f32 v[172:173], v[70:71], v[136:137], v[172:173]
	v_pk_fma_f32 v[204:205], v[74:75], v[136:137], v[204:205]
	v_pk_fma_f32 v[174:175], v[70:71], v[140:141], v[174:175]
	v_pk_fma_f32 v[206:207], v[74:75], v[140:141], v[206:207]
	ds_read_b128 v[110:113], v99 offset:17408
	ds_read_b128 v[114:117], v99 offset:21504
	ds_read_b128 v[118:121], v99 offset:25600
	ds_read_b128 v[122:125], v99 offset:29696
	s_waitcnt lgkmcnt(8)
	v_pk_mul_f32 v[176:177], v[72:73], v[142:143]
	v_pk_mul_f32 v[208:209], v[76:77], v[142:143]
	v_pk_mul_f32 v[178:179], v[72:73], v[146:147]
	v_pk_mul_f32 v[210:211], v[76:77], v[146:147]
	v_pk_mul_f32 v[180:181], v[72:73], v[150:151]
	v_pk_mul_f32 v[212:213], v[76:77], v[150:151]
	v_pk_mul_f32 v[182:183], v[72:73], v[154:155]
	v_pk_mul_f32 v[214:215], v[76:77], v[154:155]
	v_pk_fma_f32 v[176:177], v[70:71], v[144:145], v[176:177]
	v_pk_fma_f32 v[208:209], v[74:75], v[144:145], v[208:209]
	v_pk_fma_f32 v[178:179], v[70:71], v[148:149], v[178:179]
	v_pk_fma_f32 v[210:211], v[74:75], v[148:149], v[210:211]
	v_pk_fma_f32 v[180:181], v[70:71], v[152:153], v[180:181]
	v_pk_fma_f32 v[212:213], v[74:75], v[152:153], v[212:213]
	v_pk_fma_f32 v[182:183], v[70:71], v[156:157], v[182:183]
	v_pk_fma_f32 v[214:215], v[74:75], v[156:157], v[214:215]
	ds_read_b128 v[126:129], v99 offset:33792
	ds_read_b128 v[130:133], v99 offset:37888
	ds_read_b128 v[134:137], v99 offset:41984
	ds_read_b128 v[138:141], v99 offset:46080
	s_waitcnt lgkmcnt(8)
	v_pk_mul_f32 v[184:185], v[72:73], v[228:229]
	v_pk_mul_f32 v[216:217], v[76:77], v[228:229]
	v_pk_mul_f32 v[186:187], v[72:73], v[232:233]
	v_pk_mul_f32 v[218:219], v[76:77], v[232:233]
	v_pk_mul_f32 v[188:189], v[72:73], v[236:237]
	v_pk_mul_f32 v[220:221], v[76:77], v[236:237]
	v_pk_mul_f32 v[190:191], v[72:73], v[240:241]
	v_pk_mul_f32 v[222:223], v[76:77], v[240:241]
	v_pk_fma_f32 v[184:185], v[70:71], v[230:231], v[184:185]
	v_pk_fma_f32 v[216:217], v[74:75], v[230:231], v[216:217]
	v_pk_fma_f32 v[186:187], v[70:71], v[234:235], v[186:187]
	v_pk_fma_f32 v[218:219], v[74:75], v[234:235], v[218:219]
	v_pk_fma_f32 v[188:189], v[70:71], v[238:239], v[188:189]
	v_pk_fma_f32 v[220:221], v[74:75], v[238:239], v[220:221]
	v_pk_fma_f32 v[190:191], v[70:71], v[242:243], v[190:191]
	v_pk_fma_f32 v[222:223], v[74:75], v[242:243], v[222:223]
	ds_read_b128 v[142:145], v99 offset:50176
	ds_read_b128 v[146:149], v99 offset:54272
	ds_read_b128 v[150:153], v99 offset:58368
	ds_read_b128 v[154:157], v99 offset:62464
	s_waitcnt lgkmcnt(8)
	v_pk_fma_f32 v[160:161], v[64:65], v[110:111], v[160:161]
	v_pk_fma_f32 v[192:193], v[68:69], v[110:111], v[192:193]
	v_pk_fma_f32 v[162:163], v[64:65], v[114:115], v[162:163]
	v_pk_fma_f32 v[194:195], v[68:69], v[114:115], v[194:195]
	v_pk_fma_f32 v[164:165], v[64:65], v[118:119], v[164:165]
	v_pk_fma_f32 v[196:197], v[68:69], v[118:119], v[196:197]
	v_pk_fma_f32 v[166:167], v[64:65], v[122:123], v[166:167]
	v_pk_fma_f32 v[198:199], v[68:69], v[122:123], v[198:199]
	v_pk_fma_f32 v[160:161], v[30:31], v[112:113], v[160:161]
	v_pk_fma_f32 v[192:193], v[66:67], v[112:113], v[192:193]
	v_pk_fma_f32 v[162:163], v[30:31], v[116:117], v[162:163]
	v_pk_fma_f32 v[194:195], v[66:67], v[116:117], v[194:195]
	v_pk_fma_f32 v[164:165], v[30:31], v[120:121], v[164:165]
	v_pk_fma_f32 v[196:197], v[66:67], v[120:121], v[196:197]
	v_pk_fma_f32 v[166:167], v[30:31], v[124:125], v[166:167]
	v_pk_fma_f32 v[198:199], v[66:67], v[124:125], v[198:199]
	ds_read_b128 v[228:231], v100 offset:50176
	ds_read_b128 v[232:235], v100 offset:54272
	ds_read_b128 v[236:239], v100 offset:58368
	ds_read_b128 v[240:243], v100 offset:62464
	s_waitcnt lgkmcnt(8)
	v_pk_fma_f32 v[168:169], v[64:65], v[126:127], v[168:169]
	v_pk_fma_f32 v[200:201], v[68:69], v[126:127], v[200:201]
	v_pk_fma_f32 v[170:171], v[64:65], v[130:131], v[170:171]
	v_pk_fma_f32 v[202:203], v[68:69], v[130:131], v[202:203]
	v_pk_fma_f32 v[172:173], v[64:65], v[134:135], v[172:173]
	v_pk_fma_f32 v[204:205], v[68:69], v[134:135], v[204:205]
	v_pk_fma_f32 v[174:175], v[64:65], v[138:139], v[174:175]
	v_pk_fma_f32 v[206:207], v[68:69], v[138:139], v[206:207]
	v_pk_fma_f32 v[168:169], v[30:31], v[128:129], v[168:169]
	v_pk_fma_f32 v[200:201], v[66:67], v[128:129], v[200:201]
	v_pk_fma_f32 v[170:171], v[30:31], v[132:133], v[170:171]
	v_pk_fma_f32 v[202:203], v[66:67], v[132:133], v[202:203]
	v_pk_fma_f32 v[172:173], v[30:31], v[136:137], v[172:173]
	v_pk_fma_f32 v[204:205], v[66:67], v[136:137], v[204:205]
	v_pk_fma_f32 v[174:175], v[30:31], v[140:141], v[174:175]
	v_pk_fma_f32 v[206:207], v[66:67], v[140:141], v[206:207]
	ds_read_b128 v[110:113], v99 offset:18432
	ds_read_b128 v[114:117], v99 offset:22528
	ds_read_b128 v[118:121], v99 offset:26624
	ds_read_b128 v[122:125], v99 offset:30720
	s_waitcnt lgkmcnt(8)
; #define LAS __attribute__((address_space(3)))
; __device__ __forceinline__ float dot4(const f32x4 a, const f32x4 b) { return (a[0] * b[0] + a[1] * b[1]) + (a[2] * b[2] + a[3] * b[3]); }
; __device__ __forceinline__ void norm_rows2(const f32x4 (&xa)[4], const f32x4 (&xb)[4], const LAS float* gsa, const LAS float* sha, const LAS float* gsb, const LAS float* shb, const LAS float* WgT, ...
;     ...
;     for (int jq = 0; jq < 4; ++jq) { f32x4 sa = (f32x4){0.f, 0.f, 0.f, 0.f}, sb = sa;
; #pragma unroll
;         for (int i = 0; i < 4; ++i) { const LAS float* wp = WgT + (jq * 4) * 1024 + i * 256 + lane * 4;
;             const f32x4 w0 = *(const LAS f32x4*)wp, w1 = *(const LAS f32x4*)(wp + 1024), w2 = *(const LAS f32x4*)(wp + 2048), w3 = *(const LAS f32x4*)(wp + 3072);
;             sa += (f32x4){dot4(ya[i], w0), dot4(ya[i], w1), dot4(ya[i], w2), dot4(ya[i], w3)};
;             sb += (f32x4){dot4(yb[i], w0), dot4(yb[i], w1), dot4(yb[i], w2), dot4(yb[i], w3)}; }
;         pa[jq] = sa; pb[jq] = sb; }
	v_pk_fma_f32 v[176:177], v[64:65], v[142:143], v[176:177]
	v_pk_fma_f32 v[208:209], v[68:69], v[142:143], v[208:209]
	v_pk_fma_f32 v[178:179], v[64:65], v[146:147], v[178:179]
	v_pk_fma_f32 v[210:211], v[68:69], v[146:147], v[210:211]
	v_pk_fma_f32 v[180:181], v[64:65], v[150:151], v[180:181]
	v_pk_fma_f32 v[212:213], v[68:69], v[150:151], v[212:213]
	v_pk_fma_f32 v[182:183], v[64:65], v[154:155], v[182:183]
	v_pk_fma_f32 v[214:215], v[68:69], v[154:155], v[214:215]
	v_pk_fma_f32 v[176:177], v[30:31], v[144:145], v[176:177]
	v_pk_fma_f32 v[208:209], v[66:67], v[144:145], v[208:209]
	v_pk_fma_f32 v[178:179], v[30:31], v[148:149], v[178:179]
	v_pk_fma_f32 v[210:211], v[66:67], v[148:149], v[210:211]
	v_pk_fma_f32 v[180:181], v[30:31], v[152:153], v[180:181]
	v_pk_fma_f32 v[212:213], v[66:67], v[152:153], v[212:213]
	v_pk_fma_f32 v[182:183], v[30:31], v[156:157], v[182:183]
	v_pk_fma_f32 v[214:215], v[66:67], v[156:157], v[214:215]
	ds_read_b128 v[126:129], v99 offset:34816
	ds_read_b128 v[130:133], v99 offset:38912
	ds_read_b128 v[134:137], v99 offset:43008
	ds_read_b128 v[138:141], v99 offset:47104
	s_waitcnt lgkmcnt(8)
	v_pk_fma_f32 v[184:185], v[64:65], v[228:229], v[184:185]
	v_pk_fma_f32 v[216:217], v[68:69], v[228:229], v[216:217]
	v_pk_fma_f32 v[186:187], v[64:65], v[232:233], v[186:187]
	v_pk_fma_f32 v[218:219], v[68:69], v[232:233], v[218:219]
	v_pk_fma_f32 v[188:189], v[64:65], v[236:237], v[188:189]
	v_pk_fma_f32 v[220:221], v[68:69], v[236:237], v[220:221]
	v_pk_fma_f32 v[190:191], v[64:65], v[240:241], v[190:191]
	v_pk_fma_f32 v[222:223], v[68:69], v[240:241], v[222:223]
	v_pk_fma_f32 v[184:185], v[30:31], v[230:231], v[184:185]
	v_pk_fma_f32 v[216:217], v[66:67], v[230:231], v[216:217]
	v_pk_fma_f32 v[186:187], v[30:31], v[234:235], v[186:187]
	v_pk_fma_f32 v[218:219], v[66:67], v[234:235], v[218:219]
	v_pk_fma_f32 v[188:189], v[30:31], v[238:239], v[188:189]
	v_pk_fma_f32 v[220:221], v[66:67], v[238:239], v[220:221]
	v_pk_fma_f32 v[190:191], v[30:31], v[242:243], v[190:191]
	v_pk_fma_f32 v[222:223], v[66:67], v[242:243], v[222:223]
	ds_read_b128 v[142:145], v99 offset:51200
	ds_read_b128 v[146:149], v99 offset:55296
	ds_read_b128 v[150:153], v99 offset:59392
	ds_read_b128 v[154:157], v99 offset:63488
	s_waitcnt lgkmcnt(8)
	v_pk_fma_f32 v[160:161], v[20:21], v[110:111], v[160:161]
	v_pk_fma_f32 v[192:193], v[18:19], v[110:111], v[192:193]
	v_pk_fma_f32 v[162:163], v[20:21], v[114:115], v[162:163]
	v_pk_fma_f32 v[194:195], v[18:19], v[114:115], v[194:195]
	v_pk_fma_f32 v[164:165], v[20:21], v[118:119], v[164:165]
	v_pk_fma_f32 v[196:197], v[18:19], v[118:119], v[196:197]
	v_pk_fma_f32 v[166:167], v[20:21], v[122:123], v[166:167]
	v_pk_fma_f32 v[198:199], v[18:19], v[122:123], v[198:199]
	v_pk_fma_f32 v[160:161], v[16:17], v[112:113], v[160:161]
	v_pk_fma_f32 v[192:193], v[14:15], v[112:113], v[192:193]
	v_pk_fma_f32 v[162:163], v[16:17], v[116:117], v[162:163]
	v_pk_fma_f32 v[194:195], v[14:15], v[116:117], v[194:195]
	v_pk_fma_f32 v[164:165], v[16:17], v[120:121], v[164:165]
	v_pk_fma_f32 v[196:197], v[14:15], v[120:121], v[196:197]
	v_pk_fma_f32 v[166:167], v[16:17], v[124:125], v[166:167]
	v_pk_fma_f32 v[198:199], v[14:15], v[124:125], v[198:199]
	ds_read_b128 v[228:231], v100 offset:51200
	ds_read_b128 v[232:235], v100 offset:55296
	ds_read_b128 v[236:239], v100 offset:59392
	ds_read_b128 v[240:243], v100 offset:63488
	s_waitcnt lgkmcnt(8)
	v_pk_fma_f32 v[168:169], v[20:21], v[126:127], v[168:169]
	v_pk_fma_f32 v[200:201], v[18:19], v[126:127], v[200:201]
	v_pk_fma_f32 v[170:171], v[20:21], v[130:131], v[170:171]
	v_pk_fma_f32 v[202:203], v[18:19], v[130:131], v[202:203]
	v_pk_fma_f32 v[172:173], v[20:21], v[134:135], v[172:173]
	v_pk_fma_f32 v[204:205], v[18:19], v[134:135], v[204:205]
	v_pk_fma_f32 v[174:175], v[20:21], v[138:139], v[174:175]
	v_pk_fma_f32 v[206:207], v[18:19], v[138:139], v[206:207]
	v_pk_fma_f32 v[168:169], v[16:17], v[128:129], v[168:169]
	v_pk_fma_f32 v[200:201], v[14:15], v[128:129], v[200:201]
	v_pk_fma_f32 v[170:171], v[16:17], v[132:133], v[170:171]
	v_pk_fma_f32 v[202:203], v[14:15], v[132:133], v[202:203]
	v_pk_fma_f32 v[172:173], v[16:17], v[136:137], v[172:173]
	v_pk_fma_f32 v[204:205], v[14:15], v[136:137], v[204:205]
	v_pk_fma_f32 v[174:175], v[16:17], v[140:141], v[174:175]
	v_pk_fma_f32 v[206:207], v[14:15], v[140:141], v[206:207]
	ds_read_b128 v[110:113], v99 offset:19456
	ds_read_b128 v[114:117], v99 offset:23552
	ds_read_b128 v[118:121], v99 offset:27648
	ds_read_b128 v[122:125], v99 offset:31744
	s_waitcnt lgkmcnt(8)
	v_pk_fma_f32 v[176:177], v[20:21], v[142:143], v[176:177]
	v_pk_fma_f32 v[208:209], v[18:19], v[142:143], v[208:209]
	v_pk_fma_f32 v[178:179], v[20:21], v[146:147], v[178:179]
	v_pk_fma_f32 v[210:211], v[18:19], v[146:147], v[210:211]
	v_pk_fma_f32 v[180:181], v[20:21], v[150:151], v[180:181]
	v_pk_fma_f32 v[212:213], v[18:19], v[150:151], v[212:213]
	v_pk_fma_f32 v[182:183], v[20:21], v[154:155], v[182:183]
	v_pk_fma_f32 v[214:215], v[18:19], v[154:155], v[214:215]
	v_pk_fma_f32 v[176:177], v[16:17], v[144:145], v[176:177]
	v_pk_fma_f32 v[208:209], v[14:15], v[144:145], v[208:209]
	v_pk_fma_f32 v[178:179], v[16:17], v[148:149], v[178:179]
	v_pk_fma_f32 v[210:211], v[14:15], v[148:149], v[210:211]
	v_pk_fma_f32 v[180:181], v[16:17], v[152:153], v[180:181]
	v_pk_fma_f32 v[212:213], v[14:15], v[152:153], v[212:213]
	v_pk_fma_f32 v[182:183], v[16:17], v[156:157], v[182:183]
	v_pk_fma_f32 v[214:215], v[14:15], v[156:157], v[214:215]
	ds_read_b128 v[126:129], v99 offset:35840
	ds_read_b128 v[130:133], v99 offset:39936
	ds_read_b128 v[134:137], v99 offset:44032
	ds_read_b128 v[138:141], v99 offset:48128
	s_waitcnt lgkmcnt(8)
; #define LAS __attribute__((address_space(3)))
; __device__ __forceinline__ float dot4(const f32x4 a, const f32x4 b) { return (a[0] * b[0] + a[1] * b[1]) + (a[2] * b[2] + a[3] * b[3]); }
; __device__ __forceinline__ void norm_rows2(const f32x4 (&xa)[4], const f32x4 (&xb)[4], const LAS float* gsa, const LAS float* sha, const LAS float* gsb, const LAS float* shb, const LAS float* WgT, ...
;     ...
;     for (int jq = 0; jq < 4; ++jq) { f32x4 sa = (f32x4){0.f, 0.f, 0.f, 0.f}, sb = sa;
; #pragma unroll
;         for (int i = 0; i < 4; ++i) { const LAS float* wp = WgT + (jq * 4) * 1024 + i * 256 + lane * 4;
;             const f32x4 w0 = *(const LAS f32x4*)wp, w1 = *(const LAS f32x4*)(wp + 1024), w2 = *(const LAS f32x4*)(wp + 2048), w3 = *(const LAS f32x4*)(wp + 3072);
;             sa += (f32x4){dot4(ya[i], w0), dot4(ya[i], w1), dot4(ya[i], w2), dot4(ya[i], w3)};
;             sb += (f32x4){dot4(yb[i], w0), dot4(yb[i], w1), dot4(yb[i], w2), dot4(yb[i], w3)}; }
;         pa[jq] = sa; pb[jq] = sb; }
	v_pk_fma_f32 v[184:185], v[20:21], v[228:229], v[184:185]
	v_pk_fma_f32 v[216:217], v[18:19], v[228:229], v[216:217]
	v_pk_fma_f32 v[186:187], v[20:21], v[232:233], v[186:187]
	v_pk_fma_f32 v[218:219], v[18:19], v[232:233], v[218:219]
	v_pk_fma_f32 v[188:189], v[20:21], v[236:237], v[188:189]
	v_pk_fma_f32 v[220:221], v[18:19], v[236:237], v[220:221]
	v_pk_fma_f32 v[190:191], v[20:21], v[240:241], v[190:191]
	v_pk_fma_f32 v[222:223], v[18:19], v[240:241], v[222:223]
	v_pk_fma_f32 v[184:185], v[16:17], v[230:231], v[184:185]
	v_pk_fma_f32 v[216:217], v[14:15], v[230:231], v[216:217]
	v_pk_fma_f32 v[186:187], v[16:17], v[234:235], v[186:187]
	v_pk_fma_f32 v[218:219], v[14:15], v[234:235], v[218:219]
	v_pk_fma_f32 v[188:189], v[16:17], v[238:239], v[188:189]
	v_pk_fma_f32 v[220:221], v[14:15], v[238:239], v[220:221]
	v_pk_fma_f32 v[190:191], v[16:17], v[242:243], v[190:191]
	v_pk_fma_f32 v[222:223], v[14:15], v[242:243], v[222:223]
	ds_read_b128 v[142:145], v99 offset:52224
	ds_read_b128 v[146:149], v99 offset:56320
	ds_read_b128 v[150:153], v99 offset:60416
	ds_read_b128 v[154:157], v99 offset:64512
	s_waitcnt lgkmcnt(8)
	v_pk_fma_f32 v[160:161], v[8:9], v[110:111], v[160:161]
	v_pk_fma_f32 v[192:193], v[12:13], v[110:111], v[192:193]
	v_pk_fma_f32 v[162:163], v[8:9], v[114:115], v[162:163]
	v_pk_fma_f32 v[194:195], v[12:13], v[114:115], v[194:195]
	v_pk_fma_f32 v[164:165], v[8:9], v[118:119], v[164:165]
	v_pk_fma_f32 v[196:197], v[12:13], v[118:119], v[196:197]
	v_pk_fma_f32 v[166:167], v[8:9], v[122:123], v[166:167]
	v_pk_fma_f32 v[198:199], v[12:13], v[122:123], v[198:199]
	v_pk_fma_f32 v[160:161], v[6:7], v[112:113], v[160:161]
	v_pk_fma_f32 v[192:193], v[10:11], v[112:113], v[192:193]
	v_pk_fma_f32 v[162:163], v[6:7], v[116:117], v[162:163]
	v_pk_fma_f32 v[194:195], v[10:11], v[116:117], v[194:195]
	v_pk_fma_f32 v[164:165], v[6:7], v[120:121], v[164:165]
	v_pk_fma_f32 v[196:197], v[10:11], v[120:121], v[196:197]
	v_pk_fma_f32 v[166:167], v[6:7], v[124:125], v[166:167]
	v_pk_fma_f32 v[198:199], v[10:11], v[124:125], v[198:199]
	ds_read_b128 v[228:231], v100 offset:52224
	ds_read_b128 v[232:235], v100 offset:56320
	ds_read_b128 v[236:239], v100 offset:60416
	ds_read_b128 v[240:243], v100 offset:64512
	s_waitcnt lgkmcnt(8)
	v_pk_fma_f32 v[168:169], v[8:9], v[126:127], v[168:169]
	v_pk_fma_f32 v[200:201], v[12:13], v[126:127], v[200:201]
	v_pk_fma_f32 v[170:171], v[8:9], v[130:131], v[170:171]
	v_pk_fma_f32 v[202:203], v[12:13], v[130:131], v[202:203]
	v_pk_fma_f32 v[172:173], v[8:9], v[134:135], v[172:173]
	v_pk_fma_f32 v[204:205], v[12:13], v[134:135], v[204:205]
	v_pk_fma_f32 v[174:175], v[8:9], v[138:139], v[174:175]
	v_pk_fma_f32 v[206:207], v[12:13], v[138:139], v[206:207]
	v_pk_fma_f32 v[168:169], v[6:7], v[128:129], v[168:169]
	v_pk_fma_f32 v[200:201], v[10:11], v[128:129], v[200:201]
	v_pk_fma_f32 v[170:171], v[6:7], v[132:133], v[170:171]
	v_pk_fma_f32 v[202:203], v[10:11], v[132:133], v[202:203]
	v_pk_fma_f32 v[172:173], v[6:7], v[136:137], v[172:173]
	v_pk_fma_f32 v[204:205], v[10:11], v[136:137], v[204:205]
	v_pk_fma_f32 v[174:175], v[6:7], v[140:141], v[174:175]
	v_pk_fma_f32 v[206:207], v[10:11], v[140:141], v[206:207]
	s_waitcnt lgkmcnt(4)
	v_pk_fma_f32 v[176:177], v[8:9], v[142:143], v[176:177]
	v_pk_fma_f32 v[208:209], v[12:13], v[142:143], v[208:209]
	v_pk_fma_f32 v[178:179], v[8:9], v[146:147], v[178:179]
	v_pk_fma_f32 v[210:211], v[12:13], v[146:147], v[210:211]
	v_pk_fma_f32 v[180:181], v[8:9], v[150:151], v[180:181]
	v_pk_fma_f32 v[212:213], v[12:13], v[150:151], v[212:213]
	v_pk_fma_f32 v[182:183], v[8:9], v[154:155], v[182:183]
	v_pk_fma_f32 v[214:215], v[12:13], v[154:155], v[214:215]
	v_pk_fma_f32 v[176:177], v[6:7], v[144:145], v[176:177]
	v_pk_fma_f32 v[208:209], v[10:11], v[144:145], v[208:209]
	v_pk_fma_f32 v[178:179], v[6:7], v[148:149], v[178:179]
	v_pk_fma_f32 v[210:211], v[10:11], v[148:149], v[210:211]
	v_pk_fma_f32 v[180:181], v[6:7], v[152:153], v[180:181]
	v_pk_fma_f32 v[212:213], v[10:11], v[152:153], v[212:213]
	v_pk_fma_f32 v[182:183], v[6:7], v[156:157], v[182:183]
	v_pk_fma_f32 v[214:215], v[10:11], v[156:157], v[214:215]
	s_waitcnt lgkmcnt(0)
	v_pk_fma_f32 v[184:185], v[8:9], v[228:229], v[184:185]
	v_pk_fma_f32 v[216:217], v[12:13], v[228:229], v[216:217]
	v_pk_fma_f32 v[186:187], v[8:9], v[232:233], v[186:187]
	v_pk_fma_f32 v[218:219], v[12:13], v[232:233], v[218:219]
	v_pk_fma_f32 v[188:189], v[8:9], v[236:237], v[188:189]
	v_pk_fma_f32 v[220:221], v[12:13], v[236:237], v[220:221]
	v_pk_fma_f32 v[190:191], v[8:9], v[240:241], v[190:191]
	v_pk_fma_f32 v[222:223], v[12:13], v[240:241], v[222:223]
	v_pk_fma_f32 v[184:185], v[6:7], v[230:231], v[184:185]
	v_pk_fma_f32 v[216:217], v[10:11], v[230:231], v[216:217]
	v_pk_fma_f32 v[186:187], v[6:7], v[234:235], v[186:187]
	v_pk_fma_f32 v[218:219], v[10:11], v[234:235], v[218:219]
	v_pk_fma_f32 v[188:189], v[6:7], v[238:239], v[188:189]
	v_pk_fma_f32 v[220:221], v[10:11], v[238:239], v[220:221]
	v_pk_fma_f32 v[190:191], v[6:7], v[242:243], v[190:191]
	v_pk_fma_f32 v[222:223], v[10:11], v[242:243], v[222:223]
	v_add_f32_e32 v22, v160, v161
	v_add_f32_e32 v23, v162, v163
	v_add_f32_e32 v24, v164, v165
	v_add_f32_e32 v25, v166, v167
	v_add_f32_e32 v78, v168, v169
	v_add_f32_e32 v79, v170, v171
	v_add_f32_e32 v80, v172, v173
	v_add_f32_e32 v81, v174, v175
	v_add_f32_e32 v86, v176, v177
	v_add_f32_e32 v87, v178, v179
	v_add_f32_e32 v88, v180, v181
	v_add_f32_e32 v89, v182, v183
	v_add_f32_e32 v2, v184, v185
	v_add_f32_e32 v3, v186, v187
	v_add_f32_e32 v0, v188, v189
	v_add_f32_e32 v1, v190, v191
	v_add_f32_e32 v26, v192, v193
	v_add_f32_e32 v27, v194, v195
; __device__ __forceinline__ float log_sigmoid(float x) { return fminf(x, 0.f) - log1pf(expf(-fabsf(x))); }
; __device__ __forceinline__ float bfly16(const f32x4 p0, const f32x4 p1, const f32x4 p2, const f32x4 p3, int lane) {
;     const bool b3 = lane & 8, b2 = lane & 4, b1 = lane & 2, b0 = lane & 1;
;     const f32x4 s0 = b3 ? p0 : p2, s1 = b3 ? p1 : p3, k0 = b3 ? p2 : p0, k1 = b3 ? p3 : p1;
;     f32x4 a, c;
;     a[0] = k0[0] + __shfl_xor(s0[0], 8); a[1] = k0[1] + __shfl_xor(s0[1], 8); a[2] = k0[2] + __shfl_xor(s0[2], 8); a[3] = k0[3] + __shfl_xor(s0[3], 8);
;     c[0] = k1[0] + __shfl_xor(s1[0], 8); c[1] = k1[1] + __shfl_xor(s1[1], 8); c[2] = k1[2] + __shfl_xor(s1[2], 8); c[3] = k1[3] + __shfl_xor(s1[3], 8);
;     const f32x4 s4 = b2 ? a : c, k4 = b2 ? c : a;
;     const float d0 = k4[0] + __shfl_xor(s4[0], 4), d1 = k4[1] + __shfl_xor(s4[1], 4), d2 = k4[2] + __shfl_xor(s4[2], 4), d3 = k4[3] + __shfl_xor(s4[3], 4);
;     const float e0 = (b1 ? d2 : d0) + __shfl_xor(b1 ? d0 : d2, 2), e1 = (b1 ? d3 : d1) + __shfl_xor(b1 ? d1 : d3, 2);
;     float q1 = (b0 ? e1 : e0) + __shfl_xor(b0 ? e0 : e1, 1);
;     q1 += __shfl_xor(q1, 16); q1 += __shfl_xor(q1, 32);
;     return q1;
; __device__ __forceinline__ void norm_rows2(const f32x4 (&xa)[4], const f32x4 (&xb)[4], const LAS float* gsa, const LAS float* sha, const LAS float* gsb, const LAS float* shb, const LAS float* WgT, ...
;     ...
;     const float qa = bfly16(pa[0], pa[1], pa[2], pa[3], lane), qb = bfly16(pb[0], pb[1], pb[2], pb[3], lane);
;     if (lane < 16) { const float gbv = gate_b[lane]; const bool ls = (lane >> 2) & 1;
;         const float prea = qa + gbv, preb = qb + gbv;
;         ga[0] = ls ? log_sigmoid(prea) : prea; gb[0] = ls ? log_sigmoid(preb) : preb; }
	v_add_f32_e32 v28, v196, v197
	v_add_f32_e32 v29, v198, v199
	v_add_f32_e32 v82, v200, v201
	v_add_f32_e32 v83, v202, v203
	v_add_f32_e32 v84, v204, v205
	v_add_f32_e32 v85, v206, v207
	v_add_f32_e32 v90, v208, v209
	v_add_f32_e32 v91, v210, v211
	v_add_f32_e32 v92, v212, v213
	v_add_f32_e32 v93, v214, v215
	v_add_f32_e32 v12, v216, v217
	v_add_f32_e32 v13, v218, v219
	v_add_f32_e32 v10, v220, v221
	v_add_f32_e32 v11, v222, v223
	v_cndmask_b32_e64 v21, v85, v11, s[6:7]
	v_cndmask_b32_e64 v20, v84, v10, s[6:7]
	v_add_f32_dpp v110, v22, v22 row_mirror row_mask:0xf bank_mask:0x3
	v_add_f32_dpp v110, v86, v86 row_mirror row_mask:0xf bank_mask:0xc
	v_add_f32_dpp v114, v78, v78 row_mirror row_mask:0xf bank_mask:0x3
	v_add_f32_dpp v114, v2, v2 row_mirror row_mask:0xf bank_mask:0xc
	v_add_f32_dpp v118, v26, v26 row_mirror row_mask:0xf bank_mask:0x3
	v_add_f32_dpp v118, v90, v90 row_mirror row_mask:0xf bank_mask:0xc
	v_add_f32_dpp v122, v82, v82 row_mirror row_mask:0xf bank_mask:0x3
	v_add_f32_dpp v122, v12, v12 row_mirror row_mask:0xf bank_mask:0xc
	v_add_f32_dpp v111, v23, v23 row_mirror row_mask:0xf bank_mask:0x3
	v_add_f32_dpp v111, v87, v87 row_mirror row_mask:0xf bank_mask:0xc
	v_add_f32_dpp v115, v79, v79 row_mirror row_mask:0xf bank_mask:0x3
	v_add_f32_dpp v115, v3, v3 row_mirror row_mask:0xf bank_mask:0xc
	v_add_f32_dpp v119, v27, v27 row_mirror row_mask:0xf bank_mask:0x3
	v_add_f32_dpp v119, v91, v91 row_mirror row_mask:0xf bank_mask:0xc
	v_add_f32_dpp v123, v83, v83 row_mirror row_mask:0xf bank_mask:0x3
	v_add_f32_dpp v123, v13, v13 row_mirror row_mask:0xf bank_mask:0xc
	v_add_f32_dpp v112, v24, v24 row_mirror row_mask:0xf bank_mask:0x3
	v_add_f32_dpp v112, v88, v88 row_mirror row_mask:0xf bank_mask:0xc
	v_add_f32_dpp v116, v80, v80 row_mirror row_mask:0xf bank_mask:0x3
	v_add_f32_dpp v116, v0, v0 row_mirror row_mask:0xf bank_mask:0xc
	v_add_f32_dpp v120, v28, v28 row_mirror row_mask:0xf bank_mask:0x3
	v_add_f32_dpp v120, v92, v92 row_mirror row_mask:0xf bank_mask:0xc
	v_add_f32_dpp v124, v84, v84 row_mirror row_mask:0xf bank_mask:0x3
	v_add_f32_dpp v124, v10, v10 row_mirror row_mask:0xf bank_mask:0xc
	v_add_f32_dpp v113, v25, v25 row_mirror row_mask:0xf bank_mask:0x3
	v_add_f32_dpp v113, v89, v89 row_mirror row_mask:0xf bank_mask:0xc
	v_add_f32_dpp v117, v81, v81 row_mirror row_mask:0xf bank_mask:0x3
	v_add_f32_dpp v117, v1, v1 row_mirror row_mask:0xf bank_mask:0xc
	v_add_f32_dpp v121, v29, v29 row_mirror row_mask:0xf bank_mask:0x3
	v_add_f32_dpp v121, v93, v93 row_mirror row_mask:0xf bank_mask:0xc
	v_add_f32_dpp v125, v85, v85 row_mirror row_mask:0xf bank_mask:0x3
	v_add_f32_dpp v125, v11, v11 row_mirror row_mask:0xf bank_mask:0xc
	v_add_f32_dpp v126, v110, v110 row_half_mirror row_mask:0xf bank_mask:0x5
	v_add_f32_dpp v126, v114, v114 row_half_mirror row_mask:0xf bank_mask:0xa
	v_add_f32_dpp v130, v118, v118 row_half_mirror row_mask:0xf bank_mask:0x5
	v_add_f32_dpp v130, v122, v122 row_half_mirror row_mask:0xf bank_mask:0xa
	v_add_f32_dpp v127, v111, v111 row_half_mirror row_mask:0xf bank_mask:0x5
	v_add_f32_dpp v127, v115, v115 row_half_mirror row_mask:0xf bank_mask:0xa
	v_add_f32_dpp v131, v119, v119 row_half_mirror row_mask:0xf bank_mask:0x5
	v_add_f32_dpp v131, v123, v123 row_half_mirror row_mask:0xf bank_mask:0xa
	v_add_f32_dpp v128, v112, v112 row_half_mirror row_mask:0xf bank_mask:0x5
	v_add_f32_dpp v128, v116, v116 row_half_mirror row_mask:0xf bank_mask:0xa
	v_add_f32_dpp v132, v120, v120 row_half_mirror row_mask:0xf bank_mask:0x5
	v_add_f32_dpp v132, v124, v124 row_half_mirror row_mask:0xf bank_mask:0xa
	v_add_f32_dpp v129, v113, v113 row_half_mirror row_mask:0xf bank_mask:0x5
	v_add_f32_dpp v129, v117, v117 row_half_mirror row_mask:0xf bank_mask:0xa
	v_add_f32_dpp v133, v121, v121 row_half_mirror row_mask:0xf bank_mask:0x5
	v_add_f32_dpp v133, v125, v125 row_half_mirror row_mask:0xf bank_mask:0xa
	v_cndmask_b32_e64 v134, v128, v126, s[12:13]
	v_cndmask_b32_e64 v135, v126, v128, s[12:13]
	v_cndmask_b32_e64 v136, v129, v127, s[12:13]
	v_cndmask_b32_e64 v137, v127, v129, s[12:13]
	v_cndmask_b32_e64 v138, v132, v130, s[12:13]
	v_cndmask_b32_e64 v139, v130, v132, s[12:13]
	v_cndmask_b32_e64 v140, v133, v131, s[12:13]
	v_cndmask_b32_e64 v141, v131, v133, s[12:13]
	v_add_f32_dpp v134, v135, v134 quad_perm:[2,3,0,1] row_mask:0xf bank_mask:0xf
	v_add_f32_dpp v136, v137, v136 quad_perm:[2,3,0,1] row_mask:0xf bank_mask:0xf
	v_add_f32_dpp v138, v139, v138 quad_perm:[2,3,0,1] row_mask:0xf bank_mask:0xf
	v_add_f32_dpp v140, v141, v140 quad_perm:[2,3,0,1] row_mask:0xf bank_mask:0xf
	v_cndmask_b32_e64 v143, v134, v136, s[14:15]
	v_cndmask_b32_e64 v127, v138, v140, s[14:15]
	v_cndmask_b32_e64 v142, v136, v134, s[14:15]
	v_cndmask_b32_e64 v126, v140, v138, s[14:15]
	v_add_f32_dpp v1, v143, v142 quad_perm:[1,0,3,2] row_mask:0xf bank_mask:0xf
	v_add_f32_dpp v0, v127, v126 quad_perm:[1,0,3,2] row_mask:0xf bank_mask:0xf
	v_mov_b32_e32 v2, v0
	v_mov_b32_e32 v3, v1
	s_nop 1
	v_permlane16_swap_b32_e32 v2, v0
	v_permlane16_swap_b32_e32 v3, v1
	s_waitcnt lgkmcnt(0)
	v_pk_add_f32 v[0:1], v[0:1], v[2:3]
	v_mov_b32_e32 v2, v0
	v_mov_b32_e32 v3, v1
	s_nop 1
	v_permlane32_swap_b32_e32 v2, v0
	v_permlane32_swap_b32_e32 v3, v1
	s_and_saveexec_b64 s[30:31], s[16:17]
	s_cbranch_execz .LBB0_109
	s_waitcnt lgkmcnt(0)
	v_pk_add_f32 v[0:1], v[0:1], v[2:3]
	s_waitcnt vmcnt(0)
	v_pk_add_f32 v[0:1], v[0:1], v[244:245] op_sel_hi:[1,0]
	s_and_saveexec_b64 s[80:81], s[10:11]
	s_cbranch_execz .LBB0_108
; __device__ __forceinline__ float log_sigmoid(float x) { return fminf(x, 0.f) - log1pf(expf(-fabsf(x))); }
; __device__ __forceinline__ void norm_rows2(const f32x4 (&xa)[4], const f32x4 (&xb)[4], const LAS float* gsa, const LAS float* sha, const LAS float* gsb, const LAS float* shb, const LAS float* WgT, ...
;     ...
;     if (lane < 16) { const float gbv = gate_b[lane]; const bool ls = (lane >> 2) & 1;
;         const float prea = qa + gbv, preb = qb + gbv;
;         ga[0] = ls ? log_sigmoid(prea) : prea; gb[0] = ls ? log_sigmoid(preb) : preb; }
	v_mul_f32_e64 v2, |v0|, s35
	v_rndne_f32_e32 v3, v2
	v_sub_f32_e32 v4, v2, v3
	v_fma_f32 v2, |v0|, s35, -v2
	v_fma_f32 v2, |v0|, s47, v2
	v_add_f32_e32 v2, v4, v2
	v_exp_f32_e32 v4, v2
	v_cvt_i32_f32_e32 v3, v3
	v_cmp_ngt_f32_e64 s[28:29], |v0|, s53
	v_max_f32_e32 v2, v0, v0
	v_min_f32_e32 v2, 0, v2
	v_ldexp_f32 v3, v4, v3
	v_cndmask_b32_e64 v3, 0, v3, s[28:29]
	v_cmp_nlt_f32_e64 s[28:29], |v0|, s75
	s_nop 1
	v_cndmask_b32_e64 v30, v107, v3, s[28:29]
	v_add_f32_e32 v6, 1.0, v30
	v_add_f32_e32 v0, -1.0, v6
	v_sub_f32_e32 v3, v0, v6
	v_add_f32_e32 v3, 1.0, v3
	v_sub_f32_e32 v0, v30, v0
	v_add_f32_e32 v7, v0, v3
	v_mul_f32_e64 v0, |v1|, s35
	v_rndne_f32_e32 v3, v0
	v_sub_f32_e32 v9, v0, v3
	v_fma_f32 v0, |v1|, s35, -v0
	v_fma_f32 v0, |v1|, s47, v0
	v_add_f32_e32 v0, v9, v0
	v_exp_f32_e32 v0, v0
	v_cvt_i32_f32_e32 v9, v3
	v_cmp_ngt_f32_e64 s[28:29], |v1|, s53
	v_cvt_f64_f32_e32 v[4:5], v6
	v_frexp_exp_i32_f64_e32 v4, v[4:5]
	v_ldexp_f32 v0, v0, v9
	v_cndmask_b32_e64 v0, 0, v0, s[28:29]
	v_cmp_nlt_f32_e64 s[28:29], |v1|, s75
	v_max_f32_e32 v3, v1, v1
	v_frexp_mant_f32_e32 v8, v6
	v_cndmask_b32_e64 v31, v107, v0, s[28:29]
	v_add_f32_e32 v5, 1.0, v31
	v_add_f32_e32 v0, -1.0, v5
	v_sub_f32_e32 v1, v0, v5
	v_add_f32_e32 v1, 1.0, v1
	v_sub_f32_e32 v0, v31, v0
	v_add_f32_e32 v9, v0, v1
	v_frexp_mant_f32_e32 v10, v5
	v_cvt_f64_f32_e32 v[0:1], v5
	v_frexp_exp_i32_f64_e32 v0, v[0:1]
	v_cmp_gt_f32_e64 s[28:29], s79, v10
	v_min_f32_e32 v3, 0, v3
	s_nop 0
	v_subbrev_co_u32_e64 v22, s[28:29], 0, v0, s[28:29]
	v_cmp_gt_f32_e64 s[28:29], s79, v8
	s_nop 1
	v_subbrev_co_u32_e64 v23, s[28:29], 0, v4, s[28:29]
	v_sub_u32_e32 v1, 0, v23
	v_ldexp_f32 v0, v6, v1
	v_sub_u32_e32 v6, 0, v22
	v_ldexp_f32 v4, v7, v1
	v_ldexp_f32 v1, v5, v6
	v_ldexp_f32 v5, v9, v6
	v_pk_add_f32 v[6:7], v[0:1], 1.0 op_sel_hi:[1,0]
	v_pk_add_f32 v[14:15], v[0:1], -1.0 op_sel_hi:[1,0]
	v_pk_add_f32 v[8:9], v[6:7], -1.0 op_sel_hi:[1,0]
	v_pk_add_f32 v[16:17], v[14:15], 1.0 op_sel_hi:[1,0]
	v_pk_add_f32 v[8:9], v[0:1], v[8:9] neg_lo:[0,1] neg_hi:[0,1]
	v_pk_add_f32 v[0:1], v[0:1], v[16:17] neg_lo:[0,1] neg_hi:[0,1]
	v_pk_add_f32 v[8:9], v[4:5], v[8:9]
	v_pk_add_f32 v[0:1], v[4:5], v[0:1]
	v_pk_add_f32 v[10:11], v[6:7], v[8:9]
	v_pk_add_f32 v[4:5], v[14:15], v[0:1]
	v_rcp_f32_e32 v12, v10
	v_rcp_f32_e32 v13, v11
	v_pk_add_f32 v[6:7], v[6:7], v[10:11] neg_lo:[0,1] neg_hi:[0,1]
	v_pk_add_f32 v[14:15], v[14:15], v[4:5] neg_lo:[0,1] neg_hi:[0,1]
	v_pk_add_f32 v[6:7], v[8:9], v[6:7]
	v_pk_mul_f32 v[8:9], v[4:5], v[12:13]
	v_pk_add_f32 v[0:1], v[0:1], v[14:15]
	v_pk_mul_f32 v[14:15], v[10:11], v[8:9]
	v_cmp_neq_f32_e64 s[28:29], s77, v30
	v_pk_fma_f32 v[16:17], v[8:9], v[10:11], v[14:15] neg_lo:[0,0,1] neg_hi:[0,0,1]
	s_nop 0
	v_pk_fma_f32 v[16:17], v[8:9], v[6:7], v[16:17]
	s_nop 0
	v_pk_add_f32 v[18:19], v[14:15], v[16:17]
	s_nop 0
	v_pk_add_f32 v[20:21], v[4:5], v[18:19] neg_lo:[0,1] neg_hi:[0,1]
	v_pk_add_f32 v[14:15], v[18:19], v[14:15] neg_lo:[0,1] neg_hi:[0,1]
	v_pk_add_f32 v[4:5], v[4:5], v[20:21] neg_lo:[0,1] neg_hi:[0,1]
	s_nop 0
	v_pk_add_f32 v[4:5], v[4:5], v[18:19] neg_lo:[0,1] neg_hi:[0,1]
	s_nop 0
	v_pk_add_f32 v[0:1], v[0:1], v[4:5]
	v_pk_add_f32 v[4:5], v[14:15], v[16:17] neg_lo:[0,1] neg_hi:[0,1]
	s_nop 0
	v_pk_add_f32 v[0:1], v[4:5], v[0:1]
	s_nop 0
	v_pk_add_f32 v[4:5], v[20:21], v[0:1]
	s_nop 0
	v_pk_mul_f32 v[14:15], v[12:13], v[4:5]
	s_nop 0
	v_pk_mul_f32 v[16:17], v[10:11], v[14:15]
	s_nop 0
	v_pk_fma_f32 v[10:11], v[14:15], v[10:11], v[16:17] neg_lo:[0,0,1] neg_hi:[0,0,1]
	s_nop 0
	v_pk_fma_f32 v[6:7], v[14:15], v[6:7], v[10:11]
	v_pk_add_f32 v[10:11], v[20:21], v[4:5] neg_lo:[0,1] neg_hi:[0,1]
	s_nop 0
	v_pk_add_f32 v[0:1], v[0:1], v[10:11]
	v_pk_add_f32 v[10:11], v[16:17], v[6:7]
	s_nop 0
	v_pk_add_f32 v[18:19], v[4:5], v[10:11] neg_lo:[0,1] neg_hi:[0,1]
	v_pk_add_f32 v[16:17], v[10:11], v[16:17] neg_lo:[0,1] neg_hi:[0,1]
	v_pk_add_f32 v[4:5], v[4:5], v[18:19] neg_lo:[0,1] neg_hi:[0,1]
	s_nop 0
	v_pk_add_f32 v[4:5], v[4:5], v[10:11] neg_lo:[0,1] neg_hi:[0,1]
	s_nop 0
	v_pk_add_f32 v[0:1], v[0:1], v[4:5]
	v_pk_add_f32 v[4:5], v[16:17], v[6:7] neg_lo:[0,1] neg_hi:[0,1]
	s_nop 0
	v_pk_add_f32 v[0:1], v[4:5], v[0:1]
; __device__ __forceinline__ float log_sigmoid(float x) { return fminf(x, 0.f) - log1pf(expf(-fabsf(x))); }
; __device__ __forceinline__ void norm_rows2(const f32x4 (&xa)[4], const f32x4 (&xb)[4], const LAS float* gsa, const LAS float* sha, const LAS float* gsb, const LAS float* shb, const LAS float* WgT, ...
;     ...
;     if (lane < 16) { const float gbv = gate_b[lane]; const bool ls = (lane >> 2) & 1;
;         const float prea = qa + gbv, preb = qb + gbv;
;         ga[0] = ls ? log_sigmoid(prea) : prea; gb[0] = ls ? log_sigmoid(preb) : preb; }
	v_pk_add_f32 v[4:5], v[8:9], v[14:15]
	v_pk_add_f32 v[0:1], v[18:19], v[0:1]
	v_pk_add_f32 v[6:7], v[4:5], v[8:9] neg_lo:[0,1] neg_hi:[0,1]
	v_pk_mul_f32 v[0:1], v[12:13], v[0:1]
	v_pk_add_f32 v[6:7], v[14:15], v[6:7] neg_lo:[0,1] neg_hi:[0,1]
	v_cvt_f32_i32_e32 v9, v22
	v_pk_add_f32 v[0:1], v[6:7], v[0:1]
	v_cvt_f32_i32_e32 v8, v23
	v_pk_add_f32 v[6:7], v[4:5], v[0:1]
	v_pk_mul_f32 v[14:15], v[8:9], s[76:77] op_sel_hi:[1,0]
	v_pk_mul_f32 v[10:11], v[6:7], v[6:7]
	v_pk_add_f32 v[4:5], v[6:7], v[4:5] neg_lo:[0,1] neg_hi:[0,1]
	v_pk_fma_f32 v[12:13], v[10:11], s[52:53], v[52:53] op_sel_hi:[1,0,0]
	v_pk_add_f32 v[0:1], v[0:1], v[4:5] neg_lo:[0,1] neg_hi:[0,1]
	v_ldexp_f32 v4, v6, 1
	v_pk_fma_f32 v[12:13], v[10:11], v[12:13], s[74:75] op_sel_hi:[1,1,0]
	v_ldexp_f32 v5, v7, 1
	v_pk_mul_f32 v[6:7], v[6:7], v[10:11]
	v_pk_fma_f32 v[16:17], v[8:9], s[76:77], v[14:15] op_sel_hi:[1,0,1] neg_lo:[0,0,1] neg_hi:[0,0,1]
	v_pk_mul_f32 v[6:7], v[6:7], v[12:13]
	v_mov_b32_e32 v19, v5
	v_pk_add_f32 v[10:11], v[4:5], v[6:7]
	v_ldexp_f32 v0, v0, 1
	v_pk_add_f32 v[4:5], v[10:11], v[4:5] neg_lo:[0,1] neg_hi:[0,1]
	v_pk_fma_f32 v[8:9], v[8:9], s[78:79], v[16:17] op_sel_hi:[1,0,1]
	v_ldexp_f32 v1, v1, 1
	v_pk_add_f32 v[4:5], v[6:7], v[4:5] neg_lo:[0,1] neg_hi:[0,1]
	v_mov_b32_e32 v12, v14
	v_mov_b32_e32 v13, v7
	v_mov_b32_e32 v18, v8
	v_pk_add_f32 v[6:7], v[0:1], v[4:5]
	v_mov_b32_e32 v4, v14
	v_mov_b32_e32 v0, v8
	v_pk_add_f32 v[12:13], v[12:13], v[18:19]
	v_pk_add_f32 v[18:19], v[4:5], v[0:1]
	v_mov_b32_e32 v0, v10
	v_mov_b32_e32 v4, v6
	v_pk_add_f32 v[16:17], v[14:15], v[8:9]
	v_pk_add_f32 v[0:1], v[0:1], v[4:5]
	v_pk_add_f32 v[4:5], v[10:11], v[6:7]
	v_mov_b32_e32 v20, v16
	v_mov_b32_e32 v21, v15
	v_mov_b32_e32 v22, v4
	v_mov_b32_e32 v23, v9
	v_pk_add_f32 v[0:1], v[12:13], v[0:1]
	v_pk_add_f32 v[12:13], v[16:17], v[4:5]
	v_pk_add_f32 v[24:25], v[20:21], v[22:23]
	v_mov_b32_e32 v26, v4
	v_mov_b32_e32 v27, v13
	v_mov_b32_e32 v28, v10
	v_mov_b32_e32 v29, v17
	v_pk_add_f32 v[20:21], v[24:25], v[20:21] neg_lo:[0,1] neg_hi:[0,1]
	v_pk_add_f32 v[26:27], v[26:27], v[28:29] neg_lo:[0,1] neg_hi:[0,1]
	v_pk_add_f32 v[24:25], v[16:17], v[14:15] neg_lo:[0,1] neg_hi:[0,1]
	v_pk_add_f32 v[22:23], v[22:23], v[20:21] neg_lo:[0,1] neg_hi:[0,1]
	v_mov_b32_e32 v28, v16
	v_mov_b32_e32 v29, v13
	v_mov_b32_e32 v15, v27
	v_mov_b32_e32 v21, v11
	v_pk_add_f32 v[10:11], v[4:5], v[10:11] neg_lo:[0,1] neg_hi:[0,1]
	v_pk_add_f32 v[14:15], v[28:29], v[14:15] neg_lo:[0,1] neg_hi:[0,1]
	v_pk_add_f32 v[24:25], v[8:9], v[24:25] neg_lo:[0,1] neg_hi:[0,1]
	v_pk_add_f32 v[0:1], v[0:1], v[20:21] neg_lo:[0,1] neg_hi:[0,1]
	v_pk_add_f32 v[10:11], v[6:7], v[10:11] neg_lo:[0,1] neg_hi:[0,1]
	v_mov_b32_e32 v9, v17
	v_mov_b32_e32 v7, v5
	v_pk_add_f32 v[0:1], v[18:19], v[0:1] neg_lo:[0,1] neg_hi:[0,1]
	v_pk_add_f32 v[8:9], v[8:9], v[14:15] neg_lo:[0,1] neg_hi:[0,1]
	v_pk_add_f32 v[4:5], v[6:7], v[26:27] neg_lo:[0,1] neg_hi:[0,1]
	v_pk_add_f32 v[14:15], v[22:23], v[0:1]
	v_pk_add_f32 v[6:7], v[4:5], v[8:9]
	v_mov_b32_e32 v5, v1
	v_pk_add_f32 v[0:1], v[24:25], v[4:5]
	v_mov_b32_e32 v9, v23
	v_pk_add_f32 v[0:1], v[0:1], v[8:9] neg_lo:[0,1] neg_hi:[0,1]
	v_mov_b32_e32 v4, v6
	v_mov_b32_e32 v5, v15
	v_pk_add_f32 v[4:5], v[4:5], v[0:1] neg_lo:[0,1] neg_hi:[0,1]
	v_pk_add_f32 v[0:1], v[10:11], v[0:1] neg_lo:[0,1] neg_hi:[0,1]
	v_pk_add_f32 v[4:5], v[8:9], v[4:5] neg_lo:[0,1] neg_hi:[0,1]
	s_nop 0
	v_pk_add_f32 v[0:1], v[0:1], v[4:5]
	v_pk_add_f32 v[4:5], v[14:15], v[6:7]
	s_nop 0
	v_pk_add_f32 v[6:7], v[12:13], v[4:5]
	s_nop 0
	v_pk_add_f32 v[8:9], v[6:7], v[12:13] neg_lo:[0,1] neg_hi:[0,1]
	s_nop 0
	v_pk_add_f32 v[4:5], v[4:5], v[8:9] neg_lo:[0,1] neg_hi:[0,1]
	s_nop 0
	v_pk_add_f32 v[0:1], v[0:1], v[4:5]
	s_nop 0
	v_pk_add_f32 v[0:1], v[6:7], v[0:1]
	s_nop 0
	v_cndmask_b32_e64 v0, v107, v0, s[28:29]
	v_cmp_neq_f32_e64 s[28:29], s77, v31
	s_nop 1
	v_cndmask_b32_e64 v1, v107, v1, s[28:29]
	v_cmp_lt_f32_e64 s[28:29], |v31|, s92
	s_nop 1
	v_cndmask_b32_e64 v1, v1, v31, s[28:29]
	v_cmp_lt_f32_e64 s[28:29], |v30|, s92
	s_nop 1
	v_cndmask_b32_e64 v0, v0, v30, s[28:29]
	v_pk_add_f32 v[0:1], v[2:3], v[0:1] neg_lo:[0,1] neg_hi:[0,1]
	s_branch .LBB0_108
